# scan: static priority raise for the staging waves (0-3) during the decay prep, so the waves that also stage the next chunk reach the barrier sooner
# baseline (speedup 1.0000x reference)
; #define LAS __attribute__((address_space(3)))
; __device__ __forceinline__ void scan_phase(LAS unsigned char* lds, bf16* proj, int G, int bid) {
;     ...
;         for (int c = 0; c < 272; ++c) {
;             LAS unsigned char* set = lds + (c & 1) * SET;
;             SC_PREP(c + 1);
.LBB0_433:
	s_and_b64 vcc, exec, s[38:39]
	s_cbranch_vccz .Lscanprio_a
	s_setprio 1
